# combo k=2 bswap4 + phase-B in-proj 256x128 tile k-loop via LDS-DMA
# speedup vs baseline: 1.0140x; 1.0056x over previous
; DI char* opq(char* q) { size_t z = 0; asm volatile("" : "+s"(z)); return q + z; }
; DI int tidx() { int t = threadIdx.x; asm volatile("" : "+v"(t)); return t; }
; #define GLOAD(dst, kt_) _Pragma("unroll") for (int i = 0; i < NCH; ++i) { dst[i] = (i < NCHW) ? ldw(i, tid >> 3, (kt_) * 64 + (tid & 7) * 8) : ldx(i - NCHW, tid >> 3, (kt_) * 64 + (tid & 7) * 8); }
; #define LSTORE(src, base) _Pragma("unroll") for (int i = 0; i < NCH; ++i) { const int c = tid + 256 * i; *(u32x4*)((base) + (c >> 3) * 144 + (c & 7) * 16) = src[i]; }
; template <int WGN, int INS, int IMS, bool DB, class LdW, class LdX>
; DI void gemm_core(f32x16 (&acc)[INS][IMS], const int KT, LdW ldw, LdX ldx, char* lds, const int tid) {
;   constexpr int WGM = 4 / WGN;
;   constexpr int WROWS = WGN * 32 * INS, XROWS = WGM * 32 * IMS, NROWS = WROWS + XROWS, NCH = NROWS / 32, NCHW = WROWS / 32, BUFB = NROWS * 144;
;   const int lane = tid & 63, wid = tid >> 6, l31 = lane & 31, hi = lane >> 5;
;   const int wn = (WGN == 2) ? (wid >> 1) : wid, wm = (WGN == 2) ? (wid & 1) : 0;
;   const int offa = (wn * 32 * INS + l31) * 144 + hi * 16;
;   const int offb = (WROWS + wm * 32 * IMS + l31) * 144 + hi * 16;
; #pragma unroll
;   for (int a = 0; a < INS; ++a)
; #pragma unroll
;     for (int b = 0; b < IMS; ++b)
; #pragma unroll
;       for (int r = 0; r < 16; ++r) acc[a][b][r] = 0.f;
;     ...
;   if (DB) {
;     u32x4 preA[NCH], preB[NCH];
;     GLOAD(preA, 0)
;     GLOAD(preB, 1)
;     __syncthreads();
;     LSTORE(preA, lds)
;     __syncthreads();
;     for (int kt = 0; kt < KT; kt += 2) {
;       if (kt + 2 < KT) { GLOAD(preA, kt + 2) }
; template <int NTW>
; DI void inproj_tile(const Params& p, int l, int mt, int ntile, char* lds) {
;   char* const ws_ = opq(p.ws);
;   const u16* W = (const u16*)(ws_ + OFF_WIN) + ((size_t)l * NP + ntile * 64 * NTW) * 1024;
;   const u16* X = (const u16*)(ws_ + OFF_XB) + (size_t)mt * 128 * 1024;
;   f32x16 acc[NTW][2];
;   const int tid = tidx();
;   gemm_core<2, NTW, 2, (NTW == 2)>(acc, 16, [&](int i, int r0, int k) -> u32x4 { return *(const u32x4*)((W + i * 32768) + (unsigned)(r0 * 1024 + k)); },
;                [&](int i, int r0, int k) -> u32x4 { return *(const u32x4*)((X + i * 32768) + (unsigned)(r0 * 1024 + k)); }, lds, tid);
.Lb_tile:
	s_lshl_b32 s0, s36, 4
	s_and_b32 s0, s0, 0x70
	s_bfe_u32 s1, s36, 0x40003
	s_or_b32 s4, s0, s1
	s_mov_b64 s[0:1], 0
	s_add_u32 s27, s90, s0
	s_addc_u32 s37, s91, s1
	s_lshl_b32 s0, s36, 1
	s_and_b32 s0, s0, 0xffffff00
	s_addk_i32 s0, 0x800
	s_ashr_i32 s1, s0, 31
	s_add_u32 s2, s0, s28
	s_addc_u32 s3, s1, 0
	s_lshl_b64 s[2:3], s[2:3], 11
	s_add_u32 s2, s27, s2
	s_addc_u32 s3, s37, s3
	s_lshl_b32 s80, s4, 7
	s_lshl_b32 s26, s4, 18
	s_add_u32 s24, s27, s26
	s_addc_u32 s25, s37, 0
	s_add_u32 s4, s24, 0x2a40000
	s_addc_u32 s5, s25, 0
	v_mov_b32_e32 v181, v176
	v_and_b32_e32 v183, 0x5f, v181
	v_lshrrev_b32_e32 v185, 3, v181
	v_or_b32_e32 v254, s80, v183
	v_lshlrev_b32_e32 v254, 2, v254
	s_add_u32 s14, s27, 0x4a40000
	s_addc_u32 s15, s37, 0
	global_load_dword v252, v254, s[14:15]
	global_load_dword v253, v254, s[14:15] offset:128
	v_and_b32_e32 v220, 63, v181
	v_lshrrev_b32_e32 v221, 6, v181
	v_lshrrev_b32_e32 v222, 3, v220
	v_readfirstlane_b32 s13, v221
	v_and_b32_e32 v223, 7, v220
	v_bfe_u32 v224, v220, 4, 2
	v_xor_b32_e32 v223, v223, v224
	v_lshlrev_b32_e32 v223, 4, v223
	v_and_b32_e32 v224, 1, v221
	v_lshrrev_b32_e32 v225, 1, v221
	v_lshlrev_b32_e32 v224, 5, v224
	v_lshl_add_u32 v224, v225, 7, v224
	v_add_u32_e32 v224, v224, v222
	v_lshl_add_u32 v225, v221, 5, v222
	v_lshl_or_b32 v210, v224, 11, v223
	v_lshl_or_b32 v216, v225, 11, v223
	v_xor_b32_e32 v224, 64, v210
	v_xor_b32_e32 v225, 64, v216
	v_add_u32_e32 v211, 0x3c00, v224
	v_add_u32_e32 v217, 0x3c00, v225
	v_add_u32_e32 v212, 0x7800, v210
	v_add_u32_e32 v218, 0x7800, v216
	v_add_u32_e32 v213, 0xb400, v224
	v_add_u32_e32 v219, 0xb400, v225
	v_and_b32_e32 v222, 31, v220
	v_lshrrev_b32_e32 v223, 5, v220
	v_bfe_u32 v224, v220, 1, 3
	v_xor_b32_e32 v223, v223, v224
	v_lshlrev_b32_e32 v223, 4, v223
	v_lshrrev_b32_e32 v224, 1, v221
	v_and_b32_e32 v225, 1, v221
	v_lshl_add_u32 v224, v224, 6, v222
	v_lshl_add_u32 v225, v225, 6, v222
	v_lshl_or_b32 v202, v224, 7, v223
	v_lshl_or_b32 v206, v225, 7, v223
	v_xor_b32_e32 v203, 32, v202
	v_xor_b32_e32 v207, 32, v206
	v_xor_b32_e32 v204, 64, v202
	v_xor_b32_e32 v208, 64, v206
	v_xor_b32_e32 v205, 96, v202
	v_xor_b32_e32 v209, 96, v206
	s_lshl_b32 s13, s13, 12
	s_sub_u32 s10, s4, 0x80
	s_subb_u32 s11, s5, 0
	s_add_u32 s8, s2, 0x1ff80
	s_addc_u32 s9, s3, 0
	s_sub_u32 s6, s2, 0x80
	s_subb_u32 s7, s3, 0
	s_mov_b32 s12, 0
	v_mov_b32_e32 v112, 0
	v_mov_b32_e32 v113, 0
	v_mov_b32_e32 v114, 0
	v_mov_b32_e32 v115, 0
	v_mov_b32_e32 v116, 0
	v_mov_b32_e32 v117, 0
	v_mov_b32_e32 v118, 0
	v_mov_b32_e32 v119, 0
	v_mov_b32_e32 v120, 0
	v_mov_b32_e32 v121, 0
	v_mov_b32_e32 v122, 0
	v_mov_b32_e32 v123, 0
	v_mov_b32_e32 v124, 0
	v_mov_b32_e32 v125, 0
	v_mov_b32_e32 v126, 0
	v_mov_b32_e32 v127, 0
	v_mov_b32_e32 v48, 0
	v_mov_b32_e32 v49, 0
	v_mov_b32_e32 v50, 0
	v_mov_b32_e32 v51, 0
	v_mov_b32_e32 v52, 0
	v_mov_b32_e32 v53, 0
	v_mov_b32_e32 v54, 0
	v_mov_b32_e32 v55, 0
	v_mov_b32_e32 v56, 0
	v_mov_b32_e32 v57, 0
	v_mov_b32_e32 v58, 0
	v_mov_b32_e32 v59, 0
	v_mov_b32_e32 v60, 0
	v_mov_b32_e32 v61, 0
	v_mov_b32_e32 v62, 0
	v_mov_b32_e32 v63, 0
	v_mov_b32_e32 v96, 0
	v_mov_b32_e32 v97, 0
	v_mov_b32_e32 v98, 0
	v_mov_b32_e32 v99, 0
	v_mov_b32_e32 v100, 0
	v_mov_b32_e32 v101, 0
	v_mov_b32_e32 v102, 0
	v_mov_b32_e32 v103, 0
	v_mov_b32_e32 v104, 0
	v_mov_b32_e32 v105, 0
	v_mov_b32_e32 v106, 0
	v_mov_b32_e32 v107, 0
	v_mov_b32_e32 v108, 0
	v_mov_b32_e32 v109, 0
	v_mov_b32_e32 v110, 0
	v_mov_b32_e32 v111, 0
	v_mov_b32_e32 v32, 0
	v_mov_b32_e32 v33, 0
	v_mov_b32_e32 v34, 0
	v_mov_b32_e32 v35, 0
	v_mov_b32_e32 v36, 0
	v_mov_b32_e32 v37, 0
	v_mov_b32_e32 v38, 0
	v_mov_b32_e32 v39, 0
	v_mov_b32_e32 v40, 0
	v_mov_b32_e32 v41, 0
	v_mov_b32_e32 v42, 0
	v_mov_b32_e32 v43, 0
	v_mov_b32_e32 v44, 0
	v_mov_b32_e32 v45, 0
	v_mov_b32_e32 v46, 0
	v_mov_b32_e32 v47, 0
	v_mov_b32_e32 v80, 0
	v_mov_b32_e32 v81, 0
	v_mov_b32_e32 v82, 0
	v_mov_b32_e32 v83, 0
	v_mov_b32_e32 v84, 0
	v_mov_b32_e32 v85, 0
	v_mov_b32_e32 v86, 0
	v_mov_b32_e32 v87, 0
	v_mov_b32_e32 v88, 0
	v_mov_b32_e32 v89, 0
	v_mov_b32_e32 v90, 0
	v_mov_b32_e32 v91, 0
	v_mov_b32_e32 v92, 0
	v_mov_b32_e32 v93, 0
	v_mov_b32_e32 v94, 0
	v_mov_b32_e32 v95, 0
	v_mov_b32_e32 v16, 0
	v_mov_b32_e32 v17, 0
	v_mov_b32_e32 v18, 0
	v_mov_b32_e32 v19, 0
	v_mov_b32_e32 v20, 0
	v_mov_b32_e32 v21, 0
	v_mov_b32_e32 v22, 0
	v_mov_b32_e32 v23, 0
	v_mov_b32_e32 v24, 0
	v_mov_b32_e32 v25, 0
	v_mov_b32_e32 v26, 0
	v_mov_b32_e32 v27, 0
	v_mov_b32_e32 v28, 0
	v_mov_b32_e32 v29, 0
	v_mov_b32_e32 v30, 0
	v_mov_b32_e32 v31, 0
	v_mov_b32_e32 v64, 0
	v_mov_b32_e32 v65, 0
	v_mov_b32_e32 v66, 0
	v_mov_b32_e32 v67, 0
	v_mov_b32_e32 v68, 0
	v_mov_b32_e32 v69, 0
	v_mov_b32_e32 v70, 0
	v_mov_b32_e32 v71, 0
	v_mov_b32_e32 v72, 0
	v_mov_b32_e32 v73, 0
	v_mov_b32_e32 v74, 0
	v_mov_b32_e32 v75, 0
	v_mov_b32_e32 v76, 0
	v_mov_b32_e32 v77, 0
	v_mov_b32_e32 v78, 0
	v_mov_b32_e32 v79, 0
	v_mov_b32_e32 v0, 0
	v_mov_b32_e32 v1, 0
	v_mov_b32_e32 v2, 0
	v_mov_b32_e32 v3, 0
	v_mov_b32_e32 v4, 0
	v_mov_b32_e32 v5, 0
	v_mov_b32_e32 v6, 0
	v_mov_b32_e32 v7, 0
	v_mov_b32_e32 v8, 0
	v_mov_b32_e32 v9, 0
	v_mov_b32_e32 v10, 0
	v_mov_b32_e32 v11, 0
	v_mov_b32_e32 v12, 0
	v_mov_b32_e32 v13, 0
	v_mov_b32_e32 v14, 0
	v_mov_b32_e32 v15, 0
	s_waitcnt lgkmcnt(0)
	s_barrier
	s_add_u32 s10, s10, 0x80
	s_addc_u32 s11, s11, 0
	s_add_u32 m0, s13, 0
	s_nop 0
	global_load_lds_dwordx4 v216, s[10:11]
	global_load_lds_dwordx4 v217, s[10:11] offset:1024
	global_load_lds_dwordx4 v218, s[10:11] offset:2048
	global_load_lds_dwordx4 v219, s[10:11] offset:3072
	s_add_u32 s6, s6, 0x80
	s_addc_u32 s7, s7, 0
	s_add_u32 m0, s13, 32768
	s_nop 0
	global_load_lds_dwordx4 v210, s[6:7]
	global_load_lds_dwordx4 v211, s[6:7] offset:1024
	global_load_lds_dwordx4 v212, s[6:7] offset:2048
	global_load_lds_dwordx4 v213, s[6:7] offset:3072

; #define GLOAD(dst, kt_) _Pragma("unroll") for (int i = 0; i < NCH; ++i) { dst[i] = (i < NCHW) ? ldw(i, tid >> 3, (kt_) * 64 + (tid & 7) * 8) : ldx(i - NCHW, tid >> 3, (kt_) * 64 + (tid & 7) * 8); }
; #define LSTORE(src, base) _Pragma("unroll") for (int i = 0; i < NCH; ++i) { const int c = tid + 256 * i; *(u32x4*)((base) + (c >> 3) * 144 + (c & 7) * 16) = src[i]; }
; template <int WGN, int INS, int IMS, bool DB, class LdW, class LdX>
; DI void gemm_core(f32x16 (&acc)[INS][IMS], const int KT, LdW ldw, LdX ldx, char* lds, const int tid) {
;     ...
;     for (int kt = 0; kt < KT; ++kt) {
;       __syncthreads();
;       LSTORE(pre, lds)
;       __syncthreads();
;       if (kt + 1 < KT) { GLOAD(pre, kt + 1) }
;       if (INS >= 4) COMPUTE_FLAT(lds) else COMPUTE_PIPE(lds)
;     }
; template <int NTW>
; DI void inproj_tile(const Params& p, int l, int mt, int ntile, char* lds) {
;     ...
;   const int lane = tid & 63, wid = tid >> 6, l31 = lane & 31, hi = lane >> 5, wn = wid >> 1, wm = wid & 1;
;   const float* rn = (const float*)(ws_ + OFF_RN);
;   u16* proj = (u16*)(ws_ + OFF_PROJ);
;   constexpr int NCOLS = 64 * NTW, RS = NCOLS * 2 + 16;
;   __syncthreads();
; #pragma unroll
;   for (int im = 0; im < 2; ++im) {
;     const int tl = wm * 64 + im * 32 + l31;
;     const float r = rn[(size_t)mt * 128 + tl];
; #pragma unroll
;     for (int in = 0; in < NTW; ++in)
; #pragma unroll
;       for (int g = 0; g < 4; ++g) {
;         const int n = wn * 32 * NTW + in * 32 + 8 * g + 4 * hi;
;         u32x2 o; o[0] = pk2(acc[in][im][4 * g] * r, acc[in][im][4 * g + 1] * r); o[1] = pk2(acc[in][im][4 * g + 2] * r, acc[in][im][4 * g + 3] * r);
;         *(u32x2*)(lds + tl * RS + n * 2) = o;
;       }
;   }
.Lgb_p1c:
	s_waitcnt lgkmcnt(6)
	v_mfma_f32_32x32x16_bf16 v[80:95], v[128:131], v[160:163], v[80:95]
	v_mfma_f32_32x32x16_bf16 v[16:31], v[128:131], v[236:239], v[16:31]
	v_mfma_f32_32x32x16_bf16 v[64:79], v[144:147], v[160:163], v[64:79]
	v_mfma_f32_32x32x16_bf16 v[0:15], v[144:147], v[236:239], v[0:15]
	s_waitcnt lgkmcnt(4)
	v_mfma_f32_32x32x16_bf16 v[80:95], v[132:135], v[164:167], v[80:95]
	v_mfma_f32_32x32x16_bf16 v[16:31], v[132:135], v[240:243], v[16:31]
	v_mfma_f32_32x32x16_bf16 v[64:79], v[148:151], v[164:167], v[64:79]
	v_mfma_f32_32x32x16_bf16 v[0:15], v[148:151], v[240:243], v[0:15]
	s_waitcnt lgkmcnt(2)
	v_mfma_f32_32x32x16_bf16 v[80:95], v[136:139], v[168:171], v[80:95]
	v_mfma_f32_32x32x16_bf16 v[16:31], v[136:139], v[244:247], v[16:31]
	v_mfma_f32_32x32x16_bf16 v[64:79], v[152:155], v[168:171], v[64:79]
	v_mfma_f32_32x32x16_bf16 v[0:15], v[152:155], v[244:247], v[0:15]
	s_waitcnt lgkmcnt(0)
	v_mfma_f32_32x32x16_bf16 v[80:95], v[140:143], v[172:175], v[80:95]
	v_mfma_f32_32x32x16_bf16 v[16:31], v[140:143], v[248:251], v[16:31]
	v_mfma_f32_32x32x16_bf16 v[64:79], v[156:159], v[172:175], v[64:79]
	v_mfma_f32_32x32x16_bf16 v[0:15], v[156:159], v[248:251], v[0:15]
	s_add_i32 s12, s12, 1
	s_cmp_lg_u32 s12, 8
	s_cbranch_scc1 .Lgb_loop
	s_nop 15
	s_barrier
	s_add_u32 s2, s27, 0x4a40000
	s_addc_u32 s3, s37, 0
	s_lshl_b64 s[0:1], s[0:1], 1
	s_add_u32 s0, s27, s0
	s_addc_u32 s1, s37, s1
	s_add_u32 s0, s0, 0x4a50000
	s_addc_u32 s1, s1, 0
	v_and_b32_e32 v128, 0x7fffff80, v181
	v_and_or_b32 v129, v185, 4, v128
	v_or_b32_e32 v128, s80, v183
	v_lshlrev_b32_e32 v132, 2, v128
	v_mov_b32_e32 v128, v252
	s_waitcnt vmcnt(0)
	s_nop 2
	v_mul_f32_e64 v112, v112, v128
	v_mul_f32_e64 v113, v113, v128
	v_cvt_pk_bf16_f32 v130, v112, v113
	v_mul_f32_e64 v112, v114, v128
	v_mul_f32_e64 v113, v115, v128
	v_mul_f32_e64 v96, v96, v128
	v_mul_f32_e64 v97, v97, v128
	v_cvt_pk_bf16_f32 v131, v112, v113
	v_lshlrev_b32_e32 v112, 1, v129
	v_mad_u32_u24 v112, v183, s73, v112
	v_pk_mul_f32 v[98:99], v[98:99], v[128:129] op_sel_hi:[1,0]
	s_nop 2
	v_pk_mul_f32 v[64:65], v[64:65], v[128:129] op_sel_hi:[1,0]
	v_pk_mul_f32 v[66:67], v[66:67], v[128:129] op_sel_hi:[1,0]
	v_cvt_pk_bf16_f32 v64, v64, v65
	v_cvt_pk_bf16_f32 v65, v66, v67
	v_pk_mul_f32 v[66:67], v[68:69], v[128:129] op_sel_hi:[1,0]
	v_pk_mul_f32 v[68:69], v[70:71], v[128:129] op_sel_hi:[1,0]
	v_cvt_pk_bf16_f32 v66, v66, v67
	v_cvt_pk_bf16_f32 v67, v68, v69
	ds_write2_b64 v112, v[64:65], v[66:67] offset0:24 offset1:26
	v_pk_mul_f32 v[64:65], v[72:73], v[128:129] op_sel_hi:[1,0]
	v_pk_mul_f32 v[66:67], v[74:75], v[128:129] op_sel_hi:[1,0]
	v_cvt_pk_bf16_f32 v64, v64, v65
	v_cvt_pk_bf16_f32 v65, v66, v67
	v_pk_mul_f32 v[66:67], v[76:77], v[128:129] op_sel_hi:[1,0]
	v_pk_mul_f32 v[68:69], v[78:79], v[128:129] op_sel_hi:[1,0]
	v_cvt_pk_bf16_f32 v66, v66, v67
	v_cvt_pk_bf16_f32 v67, v68, v69
	ds_write2_b64 v112, v[64:65], v[66:67] offset0:28 offset1:30
	v_or_b32_e32 v64, 0x80, v132
	v_mov_b32_e32 v64, v253
	v_mul_f32_e64 v114, v116, v128
	v_mul_f32_e64 v115, v117, v128
	v_mul_f32_e64 v116, v118, v128
	v_mul_f32_e64 v117, v119, v128
	v_cvt_pk_bf16_f32 v96, v96, v97
	v_cvt_pk_bf16_f32 v97, v98, v99
	v_pk_mul_f32 v[98:99], v[100:101], v[128:129] op_sel_hi:[1,0]
	v_pk_mul_f32 v[100:101], v[102:103], v[128:129] op_sel_hi:[1,0]
	v_cvt_pk_bf16_f32 v114, v114, v115
	s_nop 1
	v_mul_f32_e64 v80, v80, v128
	v_mul_f32_e64 v81, v81, v128
	v_mul_f32_e64 v82, v82, v128
	v_mul_f32_e64 v83, v83, v128
	v_cvt_pk_bf16_f32 v80, v80, v81
	v_cvt_pk_bf16_f32 v81, v82, v83
	v_pk_mul_f32 v[82:83], v[84:85], v[128:129] op_sel_hi:[1,0]
	v_pk_mul_f32 v[84:85], v[86:87], v[128:129] op_sel_hi:[1,0]
	v_cvt_pk_bf16_f32 v115, v116, v117
	v_cvt_pk_bf16_f32 v98, v98, v99
	v_cvt_pk_bf16_f32 v99, v100, v101
	v_cvt_pk_bf16_f32 v82, v82, v83
	v_cvt_pk_bf16_f32 v83, v84, v85
	ds_write2_b64 v112, v[130:131], v[114:115] offset1:2
	v_pk_mul_f32 v[114:115], v[120:121], v[128:129] op_sel_hi:[1,0]
	v_pk_mul_f32 v[116:117], v[122:123], v[128:129] op_sel_hi:[1,0]
	ds_write2_b64 v112, v[96:97], v[98:99] offset0:8 offset1:10
	v_pk_mul_f32 v[96:97], v[104:105], v[128:129] op_sel_hi:[1,0]
	v_pk_mul_f32 v[98:99], v[106:107], v[128:129] op_sel_hi:[1,0]
	ds_write2_b64 v112, v[80:81], v[82:83] offset0:16 offset1:18
	v_pk_mul_f32 v[80:81], v[88:89], v[128:129] op_sel_hi:[1,0]
	v_pk_mul_f32 v[82:83], v[90:91], v[128:129] op_sel_hi:[1,0]
	v_cvt_pk_bf16_f32 v114, v114, v115
	v_cvt_pk_bf16_f32 v115, v116, v117
	v_pk_mul_f32 v[116:117], v[124:125], v[128:129] op_sel_hi:[1,0]
	v_pk_mul_f32 v[118:119], v[126:127], v[128:129] op_sel_hi:[1,0]
	v_cvt_pk_bf16_f32 v96, v96, v97
	v_cvt_pk_bf16_f32 v97, v98, v99
	v_pk_mul_f32 v[98:99], v[108:109], v[128:129] op_sel_hi:[1,0]
	v_pk_mul_f32 v[100:101], v[110:111], v[128:129] op_sel_hi:[1,0]
	v_cvt_pk_bf16_f32 v80, v80, v81
	v_cvt_pk_bf16_f32 v81, v82, v83
	v_pk_mul_f32 v[82:83], v[92:93], v[128:129] op_sel_hi:[1,0]
	v_pk_mul_f32 v[84:85], v[94:95], v[128:129] op_sel_hi:[1,0]
	v_cvt_pk_bf16_f32 v116, v116, v117
	v_cvt_pk_bf16_f32 v117, v118, v119
	v_cvt_pk_bf16_f32 v98, v98, v99
	v_cvt_pk_bf16_f32 v99, v100, v101
	v_cvt_pk_bf16_f32 v82, v82, v83
	v_cvt_pk_bf16_f32 v83, v84, v85
	s_mov_b32 s2, 0
	ds_write2_b64 v112, v[114:115], v[116:117] offset0:4 offset1:6
	ds_write2_b64 v112, v[96:97], v[98:99] offset0:12 offset1:14
	ds_write2_b64 v112, v[80:81], v[82:83] offset0:20 offset1:22
	s_waitcnt vmcnt(0)
; template <int NTW>
; DI void inproj_tile(const Params& p, int l, int mt, int ntile, char* lds) {
;     ...
; #pragma unroll
;   for (int im = 0; im < 2; ++im) {
;     const int tl = wm * 64 + im * 32 + l31;
;     const float r = rn[(size_t)mt * 128 + tl];
; #pragma unroll
;     for (int in = 0; in < NTW; ++in)
; #pragma unroll
;       for (int g = 0; g < 4; ++g) {
;         const int n = wn * 32 * NTW + in * 32 + 8 * g + 4 * hi;
;         u32x2 o; o[0] = pk2(acc[in][im][4 * g] * r, acc[in][im][4 * g + 1] * r); o[1] = pk2(acc[in][im][4 * g + 2] * r, acc[in][im][4 * g + 3] * r);
;         *(u32x2*)(lds + tl * RS + n * 2) = o;
;       }
;   }
;   __syncthreads();
	v_pk_mul_f32 v[48:49], v[48:49], v[64:65] op_sel_hi:[1,0]
	v_pk_mul_f32 v[50:51], v[50:51], v[64:65] op_sel_hi:[1,0]
	v_pk_mul_f32 v[32:33], v[32:33], v[64:65] op_sel_hi:[1,0]
	v_pk_mul_f32 v[34:35], v[34:35], v[64:65] op_sel_hi:[1,0]
	v_pk_mul_f32 v[16:17], v[16:17], v[64:65] op_sel_hi:[1,0]
	v_pk_mul_f32 v[18:19], v[18:19], v[64:65] op_sel_hi:[1,0]
	v_pk_mul_f32 v[0:1], v[0:1], v[64:65] op_sel_hi:[1,0]
	v_pk_mul_f32 v[2:3], v[2:3], v[64:65] op_sel_hi:[1,0]
	v_cvt_pk_bf16_f32 v48, v48, v49
	v_cvt_pk_bf16_f32 v49, v50, v51
	v_pk_mul_f32 v[50:51], v[52:53], v[64:65] op_sel_hi:[1,0]
	v_pk_mul_f32 v[52:53], v[54:55], v[64:65] op_sel_hi:[1,0]
	v_cvt_pk_bf16_f32 v32, v32, v33
	v_cvt_pk_bf16_f32 v33, v34, v35
	v_pk_mul_f32 v[34:35], v[36:37], v[64:65] op_sel_hi:[1,0]
	v_pk_mul_f32 v[36:37], v[38:39], v[64:65] op_sel_hi:[1,0]
	v_cvt_pk_bf16_f32 v16, v16, v17
	v_cvt_pk_bf16_f32 v17, v18, v19
	v_pk_mul_f32 v[18:19], v[20:21], v[64:65] op_sel_hi:[1,0]
	v_pk_mul_f32 v[20:21], v[22:23], v[64:65] op_sel_hi:[1,0]
	v_cvt_pk_bf16_f32 v0, v0, v1
	v_cvt_pk_bf16_f32 v1, v2, v3
	v_pk_mul_f32 v[2:3], v[4:5], v[64:65] op_sel_hi:[1,0]
	v_pk_mul_f32 v[4:5], v[6:7], v[64:65] op_sel_hi:[1,0]
	v_cvt_pk_bf16_f32 v50, v50, v51
	v_cvt_pk_bf16_f32 v51, v52, v53
	v_add_u32_e32 v54, 0x4000, v112
	v_cvt_pk_bf16_f32 v34, v34, v35
	v_cvt_pk_bf16_f32 v35, v36, v37
	v_cvt_pk_bf16_f32 v18, v18, v19
	v_cvt_pk_bf16_f32 v19, v20, v21
	v_cvt_pk_bf16_f32 v2, v2, v3
	v_cvt_pk_bf16_f32 v3, v4, v5
	ds_write2_b64 v54, v[48:49], v[50:51] offset0:64 offset1:66
	v_pk_mul_f32 v[48:49], v[56:57], v[64:65] op_sel_hi:[1,0]
	v_pk_mul_f32 v[50:51], v[58:59], v[64:65] op_sel_hi:[1,0]
	ds_write2_b64 v54, v[32:33], v[34:35] offset0:72 offset1:74
	v_pk_mul_f32 v[32:33], v[40:41], v[64:65] op_sel_hi:[1,0]
	v_pk_mul_f32 v[34:35], v[42:43], v[64:65] op_sel_hi:[1,0]
	ds_write2_b64 v54, v[16:17], v[18:19] offset0:80 offset1:82
	v_pk_mul_f32 v[16:17], v[24:25], v[64:65] op_sel_hi:[1,0]
	v_pk_mul_f32 v[18:19], v[26:27], v[64:65] op_sel_hi:[1,0]
	ds_write2_b64 v54, v[0:1], v[2:3] offset0:88 offset1:90
	v_pk_mul_f32 v[0:1], v[8:9], v[64:65] op_sel_hi:[1,0]
	v_pk_mul_f32 v[2:3], v[10:11], v[64:65] op_sel_hi:[1,0]
	v_cvt_pk_bf16_f32 v48, v48, v49
	v_cvt_pk_bf16_f32 v49, v50, v51
	v_pk_mul_f32 v[50:51], v[60:61], v[64:65] op_sel_hi:[1,0]
	v_pk_mul_f32 v[52:53], v[62:63], v[64:65] op_sel_hi:[1,0]
	v_cvt_pk_bf16_f32 v32, v32, v33
	v_cvt_pk_bf16_f32 v33, v34, v35
	v_pk_mul_f32 v[34:35], v[44:45], v[64:65] op_sel_hi:[1,0]
	v_pk_mul_f32 v[36:37], v[46:47], v[64:65] op_sel_hi:[1,0]
	v_cvt_pk_bf16_f32 v16, v16, v17
	v_cvt_pk_bf16_f32 v17, v18, v19
	v_pk_mul_f32 v[18:19], v[28:29], v[64:65] op_sel_hi:[1,0]
	v_pk_mul_f32 v[20:21], v[30:31], v[64:65] op_sel_hi:[1,0]
	v_cvt_pk_bf16_f32 v0, v0, v1
	v_cvt_pk_bf16_f32 v1, v2, v3
	v_pk_mul_f32 v[2:3], v[12:13], v[64:65] op_sel_hi:[1,0]
	v_pk_mul_f32 v[4:5], v[14:15], v[64:65] op_sel_hi:[1,0]
	v_cvt_pk_bf16_f32 v50, v50, v51
	v_cvt_pk_bf16_f32 v51, v52, v53
	v_cvt_pk_bf16_f32 v34, v34, v35
	v_cvt_pk_bf16_f32 v35, v36, v37
	v_cvt_pk_bf16_f32 v18, v18, v19
	v_cvt_pk_bf16_f32 v19, v20, v21
	v_cvt_pk_bf16_f32 v2, v2, v3
	v_cvt_pk_bf16_f32 v3, v4, v5
	ds_write2_b64 v54, v[48:49], v[50:51] offset0:68 offset1:70
	ds_write2_b64 v54, v[32:33], v[34:35] offset0:76 offset1:78
	ds_write2_b64 v54, v[16:17], v[18:19] offset0:84 offset1:86
	ds_write2_b64 v54, v[0:1], v[2:3] offset0:92 offset1:94
	s_waitcnt lgkmcnt(0)
	s_barrier
